# P2 beta/alpha skinny GEMM tail hand-written: each 16x16 task split by K quarter over four waves, 32 loads in flight, partial sums combined through LDS (on v61)
# speedup vs baseline: 1.0034x; 1.0034x over previous
; __device__ __forceinline__ f32x4 skinny16(const bf16_t* A, int lda, const bf16_t* Bt, int ldb, int K, int lane) {
;     const int r = lane & 15, q = lane >> 4;
;     const bf16x8* ap = (const bf16x8*)(A + (size_t)r * lda + q * 8);
;     const bf16x8* bp = (const bf16x8*)(Bt + (size_t)r * ldb + q * 8);
;     f32x4 acc0 = {0.f, 0.f, 0.f, 0.f}, acc1 = {0.f, 0.f, 0.f, 0.f};
; #pragma unroll 1
;     for (int k = 0; k < K / 32; k += 16) {
;         bf16x8 a[16], b[16];
; #pragma unroll
;         for (int i = 0; i < 16; ++i) { a[i] = ap[(k + i) * 4]; b[i] = bp[(k + i) * 4]; }
; #pragma unroll
;         for (int i = 0; i < 16; i += 2) { acc0 = __builtin_amdgcn_mfma_f32_16x16x32_bf16(a[i], b[i], acc0, 0, 0, 0); acc1 = __builtin_amdgcn_mfma_f32_16x16x32_bf16(a[i + 1], b[i + 1], acc1, 0, 0, 0); }
;     }
;     return acc0 + acc1;
; }
; __global__ void __launch_bounds__(512, 2) mega(Args a) {
;     ...
;             for (int task = wave * G + bx; task < 8 + MP / 16; task += NGW) {
;                 if (task < 8) { const int mt = task;
;                     const f32x4 acc = skinny16(hb + (size_t)(MP + mt * 16) * DM, DM, Wi + (size_t)NZ * DM, DM, DM, lane);
; #pragma unroll
;                     for (int j = 0; j < 4; ++j) zs[(size_t)(mt * 16 + q8 * 4 + j) * DINP + NZ + r] = acc[j];
;                 } else { const int pt = task - 8;
;                     const f32x4 acc = skinny16(hb + (size_t)pt * 16 * DM, DM, Wi + (size_t)NZ * DM, DM, DM, lane);
; #pragma unroll
;                     for (int j = 0; j < 4; ++j) ba[(size_t)(pt * 16 + q8 * 4 + j) * 16 + r] = acc[j];
.LBB0_358:
	s_waitcnt vmcnt(0) lgkmcnt(0)
	s_load_dwordx2 s[22:23], s[0:1], 0x98
	s_lshr_b32 s4, s3, 6
	s_lshr_b32 s5, s4, 2
	s_and_b32 s6, s4, 3
	v_mbcnt_lo_u32_b32 v186, -1, 0
	v_mbcnt_hi_u32_b32 v186, -1, v186
	v_and_b32_e32 v187, 15, v186
	v_lshrrev_b32_e32 v188, 4, v186
	v_lshlrev_b32_e32 v184, 12, v187
	v_lshl_add_u32 v184, v188, 4, v184
	s_lshl_b32 s16, s6, 10
	v_add_u32_e32 v184, s16, v184
	s_mul_i32 s7, s5, 0xc00
	s_add_u32 s7, s7, 0x12000
	s_max_u32 s16, s6, 1
	s_sub_u32 s16, s16, 1
	s_lshl_b32 s16, s16, 10
	s_add_u32 s16, s16, s7
	v_lshl_add_u32 v185, v186, 4, s16
	s_lshl_b32 s18, s5, 8
	s_add_u32 s18, s18, s2
	s_mov_b32 s19, 0
	s_waitcnt lgkmcnt(0)
	s_mul_i32 s16, s92, 0x2020000
	s_add_u32 s16, s16, 0x2000000
	s_add_u32 s24, s22, s16
	s_addc_u32 s25, s23, 0
.Lsk_round:
	s_lshl_b32 s16, s18, 16
	s_cmp_lt_u32 s18, 8
	s_cbranch_scc1 .Lsk_a_s
	s_add_u32 s16, s16, 0x11a80000
	s_branch .Lsk_a_d
.Lsk_a_s:
	s_add_u32 s16, s16, 0x13b00000
.Lsk_a_d:
	s_add_u32 s26, s22, s16
	s_addc_u32 s27, s23, 0
	global_load_dwordx4 v[0:3], v184, s[26:27]
	global_load_dwordx4 v[68:71], v184, s[24:25]
	global_load_dwordx4 v[4:7], v184, s[26:27] offset:64
	global_load_dwordx4 v[72:75], v184, s[24:25] offset:64
	global_load_dwordx4 v[8:11], v184, s[26:27] offset:128
	global_load_dwordx4 v[80:83], v184, s[24:25] offset:128
	global_load_dwordx4 v[12:15], v184, s[26:27] offset:192
	global_load_dwordx4 v[84:87], v184, s[24:25] offset:192
	global_load_dwordx4 v[16:19], v184, s[26:27] offset:256
	global_load_dwordx4 v[88:91], v184, s[24:25] offset:256
	global_load_dwordx4 v[20:23], v184, s[26:27] offset:320
	global_load_dwordx4 v[92:95], v184, s[24:25] offset:320
	global_load_dwordx4 v[24:27], v184, s[26:27] offset:384
	global_load_dwordx4 v[96:99], v184, s[24:25] offset:384
	global_load_dwordx4 v[28:31], v184, s[26:27] offset:448
	global_load_dwordx4 v[100:103], v184, s[24:25] offset:448
	global_load_dwordx4 v[32:35], v184, s[26:27] offset:512
	global_load_dwordx4 v[104:107], v184, s[24:25] offset:512
	global_load_dwordx4 v[36:39], v184, s[26:27] offset:576
	global_load_dwordx4 v[108:111], v184, s[24:25] offset:576
	global_load_dwordx4 v[40:43], v184, s[26:27] offset:640
	global_load_dwordx4 v[116:119], v184, s[24:25] offset:640
	global_load_dwordx4 v[44:47], v184, s[26:27] offset:704
	global_load_dwordx4 v[120:123], v184, s[24:25] offset:704
	global_load_dwordx4 v[52:55], v184, s[26:27] offset:768
	global_load_dwordx4 v[124:127], v184, s[24:25] offset:768
	global_load_dwordx4 v[56:59], v184, s[26:27] offset:832
	global_load_dwordx4 v[128:131], v184, s[24:25] offset:832
	global_load_dwordx4 v[60:63], v184, s[26:27] offset:896
	global_load_dwordx4 v[132:135], v184, s[24:25] offset:896
	global_load_dwordx4 v[64:67], v184, s[26:27] offset:960
	global_load_dwordx4 v[136:139], v184, s[24:25] offset:960
	v_mov_b32_e32 v164, 0
	v_mov_b32_e32 v165, 0
	v_mov_b32_e32 v166, 0
	v_mov_b32_e32 v167, 0
	v_mov_b32_e32 v168, 0
	v_mov_b32_e32 v169, 0
	v_mov_b32_e32 v170, 0
	v_mov_b32_e32 v171, 0
	s_waitcnt vmcnt(30)
	v_mfma_f32_16x16x32_bf16 v[164:167], v[0:3], v[68:71], v[164:167]
	s_waitcnt vmcnt(28)
	v_mfma_f32_16x16x32_bf16 v[168:171], v[4:7], v[72:75], v[168:171]
	s_waitcnt vmcnt(26)
	v_mfma_f32_16x16x32_bf16 v[164:167], v[8:11], v[80:83], v[164:167]
	s_waitcnt vmcnt(24)
	v_mfma_f32_16x16x32_bf16 v[168:171], v[12:15], v[84:87], v[168:171]
	s_waitcnt vmcnt(22)
	v_mfma_f32_16x16x32_bf16 v[164:167], v[16:19], v[88:91], v[164:167]
	s_waitcnt vmcnt(20)
	v_mfma_f32_16x16x32_bf16 v[168:171], v[20:23], v[92:95], v[168:171]
	s_waitcnt vmcnt(18)
	v_mfma_f32_16x16x32_bf16 v[164:167], v[24:27], v[96:99], v[164:167]
	s_waitcnt vmcnt(16)
	v_mfma_f32_16x16x32_bf16 v[168:171], v[28:31], v[100:103], v[168:171]
	s_waitcnt vmcnt(14)
	v_mfma_f32_16x16x32_bf16 v[164:167], v[32:35], v[104:107], v[164:167]
	s_waitcnt vmcnt(12)
	v_mfma_f32_16x16x32_bf16 v[168:171], v[36:39], v[108:111], v[168:171]
	s_waitcnt vmcnt(10)
	v_mfma_f32_16x16x32_bf16 v[164:167], v[40:43], v[116:119], v[164:167]
	s_waitcnt vmcnt(8)
	v_mfma_f32_16x16x32_bf16 v[168:171], v[44:47], v[120:123], v[168:171]
	s_waitcnt vmcnt(6)
	v_mfma_f32_16x16x32_bf16 v[164:167], v[52:55], v[124:127], v[164:167]
	s_waitcnt vmcnt(4)
	v_mfma_f32_16x16x32_bf16 v[168:171], v[56:59], v[128:131], v[168:171]
	s_waitcnt vmcnt(2)
	v_mfma_f32_16x16x32_bf16 v[164:167], v[60:63], v[132:135], v[164:167]
	s_waitcnt vmcnt(0)
	v_mfma_f32_16x16x32_bf16 v[168:171], v[64:67], v[136:139], v[168:171]
	s_nop 7
	s_nop 7
	v_pk_add_f32 v[164:165], v[164:165], v[168:169]
	v_pk_add_f32 v[166:167], v[166:167], v[170:171]
	s_cmp_eq_u32 s6, 0
	s_cbranch_scc1 .Lsk_bar
	ds_write_b128 v185, v[164:167]
; __global__ void __launch_bounds__(512, 2) mega(Args a) {
;     ...
;             for (int task = wave * G + bx; task < 8 + MP / 16; task += NGW) {
;                 if (task < 8) { const int mt = task;
;                     const f32x4 acc = skinny16(hb + (size_t)(MP + mt * 16) * DM, DM, Wi + (size_t)NZ * DM, DM, DM, lane);
; #pragma unroll
;                     for (int j = 0; j < 4; ++j) zs[(size_t)(mt * 16 + q8 * 4 + j) * DINP + NZ + r] = acc[j];
;                 } else { const int pt = task - 8;
;                     const f32x4 acc = skinny16(hb + (size_t)pt * 16 * DM, DM, Wi + (size_t)NZ * DM, DM, DM, lane);
; #pragma unroll
;                     for (int j = 0; j < 4; ++j) ba[(size_t)(pt * 16 + q8 * 4 + j) * 16 + r] = acc[j];
;                 }
;             }
.Lsk_bar:
	s_waitcnt lgkmcnt(0)
	s_barrier
	s_cmp_eq_u32 s6, 0
	s_cbranch_scc0 .Lsk_next
	ds_read_b128 v[172:175], v185
	ds_read_b128 v[176:179], v185 offset:1024
	ds_read_b128 v[180:183], v185 offset:2048
	s_cmp_lt_u32 s18, 8
	s_cbranch_scc1 .Lsk_o_s
	s_sub_u32 s16, s18, 8
	s_lshl_b32 s16, s16, 10
	s_add_u32 s16, s16, 0x1c100000
	s_add_u32 s28, s22, s16
	s_addc_u32 s29, s23, 0
	v_lshlrev_b32_e32 v189, 8, v188
	v_lshl_add_u32 v189, v187, 2, v189
	s_waitcnt lgkmcnt(0)
	v_pk_add_f32 v[172:173], v[172:173], v[176:177]
	v_pk_add_f32 v[164:165], v[164:165], v[180:181]
	v_pk_add_f32 v[174:175], v[174:175], v[178:179]
	v_pk_add_f32 v[166:167], v[166:167], v[182:183]
	v_pk_add_f32 v[164:165], v[164:165], v[172:173]
	v_pk_add_f32 v[166:167], v[166:167], v[174:175]
	global_store_dword v189, v164, s[28:29]
	global_store_dword v189, v165, s[28:29] offset:64
	global_store_dword v189, v166, s[28:29] offset:128
	global_store_dword v189, v167, s[28:29] offset:192
	s_branch .Lsk_next
.Lsk_o_s:
	s_mul_i32 s16, s18, 0x80800
	s_add_u32 s16, s16, 0x1bc08000
	s_add_u32 s28, s22, s16
	s_addc_u32 s29, s23, 0
	v_mul_u32_u24_e32 v189, 0x20200, v188
	v_lshl_add_u32 v189, v187, 2, v189
	v_add_u32_e32 v190, 0x8080, v189
	v_add_u32_e32 v191, 0x10100, v189
	v_add_u32_e32 v186, 0x18180, v189
	s_waitcnt lgkmcnt(0)
	v_pk_add_f32 v[172:173], v[172:173], v[176:177]
	v_pk_add_f32 v[164:165], v[164:165], v[180:181]
	v_pk_add_f32 v[174:175], v[174:175], v[178:179]
	v_pk_add_f32 v[166:167], v[166:167], v[182:183]
	v_pk_add_f32 v[164:165], v[164:165], v[172:173]
	v_pk_add_f32 v[166:167], v[166:167], v[174:175]
	global_store_dword v189, v164, s[28:29]
	global_store_dword v190, v165, s[28:29]
	global_store_dword v191, v166, s[28:29]
	global_store_dword v186, v167, s[28:29]
.Lsk_next:
	s_cmp_lt_u32 s2, 8
	s_cbranch_scc0 .Lsk_done
	s_cmp_eq_u32 s19, 0
	s_cbranch_scc0 .Lsk_done
	s_mov_b32 s19, 1
	v_add_u32_e32 v185, 0x2000, v185
	s_add_u32 s18, s2, 0x200
	s_cmp_eq_u32 s5, 0
	s_cbranch_scc1 .Lsk_round
	s_barrier
.Lsk_done:
.LBB0_369:
	s_mov_b64 s[4:5], s[0:1]
	s_mov_b32 s6, s2
	s_nop 0
	v_mov_b64_e32 v[0:1], s[4:5]
	flat_load_dwordx2 v[0:1], v[0:1] offset:152
	s_getreg_b32 s4, hwreg(HW_REG_XCC_ID, 0, 4)
	s_waitcnt vmcnt(0)
	s_waitcnt vmcnt(0) lgkmcnt(0)
	s_barrier
	s_mov_b64 s[52:53], exec
	v_readlane_b32 s6, v254, 0
	v_readlane_b32 s7, v254, 1
	s_and_b64 s[6:7], s[52:53], s[6:7]
	s_mov_b64 exec, s[6:7]
	s_cbranch_execz .LBB0_413
	v_mov_b32_e32 v2, s54
	s_waitcnt vmcnt(0) expcnt(0) lgkmcnt(0)
	ds_read_b32 v6, v2
	v_mov_b32_e32 v2, s94
	ds_read_b32 v4, v2
	s_and_b32 s38, s4, 15
	s_waitcnt lgkmcnt(1)
	v_cmp_ne_u32_e32 vcc, 0, v6
	s_cbranch_vccnz .LBB0_384
	s_mov_b64 s[4:5], 0x28d00200
	v_lshl_add_u64 v[2:3], v[0:1], 0, s[4:5]
	s_mov_b64 s[4:5], 0x28d00400
	s_waitcnt lgkmcnt(0)
	v_lshl_add_u64 v[4:5], v[0:1], 0, s[4:5]
	s_mov_b64 s[4:5], 0x28d00500
	v_lshl_add_u64 v[6:7], v[0:1], 0, s[4:5]
	s_mov_b64 s[4:5], 0x28d00600
	v_lshl_add_u64 v[8:9], v[0:1], 0, s[4:5]
	s_mov_b64 s[4:5], 0x28d00700
	v_lshl_add_u64 v[10:11], v[0:1], 0, s[4:5]
	s_mov_b64 s[4:5], 0x28d00800
	v_lshl_add_u64 v[12:13], v[0:1], 0, s[4:5]
	s_mov_b64 s[4:5], 0x28d00900
	v_lshl_add_u64 v[14:15], v[0:1], 0, s[4:5]
	s_mov_b64 s[4:5], 0x28d00a00
	v_lshl_add_u64 v[16:17], v[0:1], 0, s[4:5]
	s_mov_b64 s[4:5], 0x28d00b00
	v_lshl_add_u64 v[18:19], v[0:1], 0, s[4:5]
	s_mov_b64 s[4:5], 0x28d00c00
	v_lshl_add_u64 v[20:21], v[0:1], 0, s[4:5]
	s_mov_b64 s[4:5], 0x28d00d00
	v_lshl_add_u64 v[22:23], v[0:1], 0, s[4:5]
	s_mov_b64 s[4:5], 0x28d00e00
	v_lshl_add_u64 v[24:25], v[0:1], 0, s[4:5]
	s_mov_b64 s[4:5], 0x28d00f00
	v_lshl_add_u64 v[26:27], v[0:1], 0, s[4:5]
	s_mov_b64 s[4:5], 0x28d01000
	v_lshl_add_u64 v[28:29], v[0:1], 0, s[4:5]
	s_mov_b64 s[4:5], 0x28d01100
	v_lshl_add_u64 v[30:31], v[0:1], 0, s[4:5]
	s_mov_b64 s[4:5], 0x28d01200
	v_lshl_add_u64 v[32:33], v[0:1], 0, s[4:5]
	s_mov_b64 s[4:5], 0x28d01300
	v_lshl_add_u64 v[34:35], v[0:1], 0, s[4:5]
	s_mov_b32 s24, 1
	s_mov_b64 s[4:5], 0
	s_branch .LBB0_374
